# w_in epilogue: branch-free hand-written path for the k / v column tiles of prompt rows (f32 output rows + bf16 cache rows, 48 dwordx4 stores per lane) instead of the compiler's branchy per-block code
# speedup vs baseline: 1.0101x; 1.0000x over previous
.Lwin_kv:
	s_cmp_gt_u32 s14, 255
	s_cbranch_scc1 .Lwin_slow
	s_cmp_eq_u32 s12, 4
	s_mov_b32 s60, 0x34e00000
	s_mov_b32 s100, 0x14200000
	s_cselect_b32 s60, 0x32e00000, s60
	s_cselect_b32 s100, 0x10200000, s100
	s_add_u32 s60, s22, s60
	s_addc_u32 s61, s23, 0
	s_add_u32 s100, s20, s100
	s_addc_u32 s101, s21, 0
	s_lshl_b32 s56, s14, 17
	s_add_u32 s60, s60, s56
	s_addc_u32 s61, s61, 0
	s_lshl_b32 s56, s14, 18
	s_add_u32 s100, s100, s56
	s_addc_u32 s101, s101, 0
	v_lshlrev_b32_e32 v174, 9, v149
	v_lshl_add_u32 v174, v146, 1, v174
	v_lshlrev_b32_e32 v175, 10, v149
	v_lshl_add_u32 v175, v146, 2, v175
	global_store_dwordx4 v175, v[124:127], s[100:101]
	global_store_dwordx4 v175, v[120:123], s[100:101] offset:16
	v_cvt_pk_bf16_f32 v128, v124, v125
	v_cvt_pk_bf16_f32 v129, v126, v127
	v_cvt_pk_bf16_f32 v130, v120, v121
	v_cvt_pk_bf16_f32 v131, v122, v123
	global_store_dwordx4 v174, v[128:131], s[60:61]
	global_store_dwordx4 v175, v[116:119], s[100:101] offset:512
	global_store_dwordx4 v175, v[112:115], s[100:101] offset:528
	v_cvt_pk_bf16_f32 v132, v116, v117
	v_cvt_pk_bf16_f32 v133, v118, v119
	v_cvt_pk_bf16_f32 v134, v112, v113
	v_cvt_pk_bf16_f32 v135, v114, v115
	global_store_dwordx4 v174, v[132:135], s[60:61] offset:256
	s_add_u32 s60, s60, 0x2000
	s_addc_u32 s61, s61, 0
	s_add_u32 s100, s100, 0x4000
	s_addc_u32 s101, s101, 0
	global_store_dwordx4 v175, v[108:111], s[100:101]
	global_store_dwordx4 v175, v[104:107], s[100:101] offset:16
	v_cvt_pk_bf16_f32 v128, v108, v109
	v_cvt_pk_bf16_f32 v129, v110, v111
	v_cvt_pk_bf16_f32 v130, v104, v105
	v_cvt_pk_bf16_f32 v131, v106, v107
	global_store_dwordx4 v174, v[128:131], s[60:61]
	global_store_dwordx4 v175, v[100:103], s[100:101] offset:512
	global_store_dwordx4 v175, v[96:99], s[100:101] offset:528
	v_cvt_pk_bf16_f32 v132, v100, v101
	v_cvt_pk_bf16_f32 v133, v102, v103
	v_cvt_pk_bf16_f32 v134, v96, v97
	v_cvt_pk_bf16_f32 v135, v98, v99
	global_store_dwordx4 v174, v[132:135], s[60:61] offset:256
	s_add_u32 s60, s60, 0x2000
	s_addc_u32 s61, s61, 0
	s_add_u32 s100, s100, 0x4000
	s_addc_u32 s101, s101, 0
	global_store_dwordx4 v175, v[92:95], s[100:101]
	global_store_dwordx4 v175, v[88:91], s[100:101] offset:16
	v_cvt_pk_bf16_f32 v128, v92, v93
	v_cvt_pk_bf16_f32 v129, v94, v95
	v_cvt_pk_bf16_f32 v130, v88, v89
	v_cvt_pk_bf16_f32 v131, v90, v91
	global_store_dwordx4 v174, v[128:131], s[60:61]
	global_store_dwordx4 v175, v[84:87], s[100:101] offset:512
	global_store_dwordx4 v175, v[80:83], s[100:101] offset:528
	v_cvt_pk_bf16_f32 v132, v84, v85
	v_cvt_pk_bf16_f32 v133, v86, v87
	v_cvt_pk_bf16_f32 v134, v80, v81
	v_cvt_pk_bf16_f32 v135, v82, v83
	global_store_dwordx4 v174, v[132:135], s[60:61] offset:256
	s_add_u32 s60, s60, 0x2000
	s_addc_u32 s61, s61, 0
	s_add_u32 s100, s100, 0x4000
	s_addc_u32 s101, s101, 0
	global_store_dwordx4 v175, v[76:79], s[100:101]
	global_store_dwordx4 v175, v[72:75], s[100:101] offset:16
	v_cvt_pk_bf16_f32 v128, v76, v77
	v_cvt_pk_bf16_f32 v129, v78, v79
	v_cvt_pk_bf16_f32 v130, v72, v73
	v_cvt_pk_bf16_f32 v131, v74, v75
	global_store_dwordx4 v174, v[128:131], s[60:61]
	global_store_dwordx4 v175, v[68:71], s[100:101] offset:512
	global_store_dwordx4 v175, v[64:67], s[100:101] offset:528
	v_cvt_pk_bf16_f32 v132, v68, v69
	v_cvt_pk_bf16_f32 v133, v70, v71
	v_cvt_pk_bf16_f32 v134, v64, v65
	v_cvt_pk_bf16_f32 v135, v66, v67
	global_store_dwordx4 v174, v[132:135], s[60:61] offset:256
	s_add_u32 s60, s60, 0xa000
	s_addc_u32 s61, s61, 0
	s_add_u32 s100, s100, 0x14000
	s_addc_u32 s101, s101, 0
	global_store_dwordx4 v175, v[60:63], s[100:101]
	global_store_dwordx4 v175, v[56:59], s[100:101] offset:16
	v_cvt_pk_bf16_f32 v128, v60, v61
	v_cvt_pk_bf16_f32 v129, v62, v63
	v_cvt_pk_bf16_f32 v130, v56, v57
	v_cvt_pk_bf16_f32 v131, v58, v59
	global_store_dwordx4 v174, v[128:131], s[60:61]
	global_store_dwordx4 v175, v[52:55], s[100:101] offset:512
	global_store_dwordx4 v175, v[48:51], s[100:101] offset:528
	v_cvt_pk_bf16_f32 v132, v52, v53
	v_cvt_pk_bf16_f32 v133, v54, v55
	v_cvt_pk_bf16_f32 v134, v48, v49
	v_cvt_pk_bf16_f32 v135, v50, v51
	global_store_dwordx4 v174, v[132:135], s[60:61] offset:256
	s_add_u32 s60, s60, 0x2000
	s_addc_u32 s61, s61, 0
	s_add_u32 s100, s100, 0x4000
	s_addc_u32 s101, s101, 0
	global_store_dwordx4 v175, v[44:47], s[100:101]
	global_store_dwordx4 v175, v[40:43], s[100:101] offset:16
	v_cvt_pk_bf16_f32 v128, v44, v45
	v_cvt_pk_bf16_f32 v129, v46, v47
	v_cvt_pk_bf16_f32 v130, v40, v41
	v_cvt_pk_bf16_f32 v131, v42, v43
	global_store_dwordx4 v174, v[128:131], s[60:61]
	global_store_dwordx4 v175, v[36:39], s[100:101] offset:512
	global_store_dwordx4 v175, v[32:35], s[100:101] offset:528
	v_cvt_pk_bf16_f32 v132, v36, v37
	v_cvt_pk_bf16_f32 v133, v38, v39
	v_cvt_pk_bf16_f32 v134, v32, v33
	v_cvt_pk_bf16_f32 v135, v34, v35
	global_store_dwordx4 v174, v[132:135], s[60:61] offset:256
	s_add_u32 s60, s60, 0x2000
	s_addc_u32 s61, s61, 0
	s_add_u32 s100, s100, 0x4000
	s_addc_u32 s101, s101, 0
	global_store_dwordx4 v175, v[28:31], s[100:101]
	global_store_dwordx4 v175, v[24:27], s[100:101] offset:16
	v_cvt_pk_bf16_f32 v128, v28, v29
	v_cvt_pk_bf16_f32 v129, v30, v31
	v_cvt_pk_bf16_f32 v130, v24, v25
	v_cvt_pk_bf16_f32 v131, v26, v27
	global_store_dwordx4 v174, v[128:131], s[60:61]
	global_store_dwordx4 v175, v[20:23], s[100:101] offset:512
	global_store_dwordx4 v175, v[16:19], s[100:101] offset:528
	v_cvt_pk_bf16_f32 v132, v20, v21
	v_cvt_pk_bf16_f32 v133, v22, v23
	v_cvt_pk_bf16_f32 v134, v16, v17
	v_cvt_pk_bf16_f32 v135, v18, v19
	global_store_dwordx4 v174, v[132:135], s[60:61] offset:256
	s_add_u32 s60, s60, 0x2000
	s_addc_u32 s61, s61, 0
	s_add_u32 s100, s100, 0x4000
	s_addc_u32 s101, s101, 0
	global_store_dwordx4 v175, v[12:15], s[100:101]
	global_store_dwordx4 v175, v[8:11], s[100:101] offset:16
	v_cvt_pk_bf16_f32 v128, v12, v13
	v_cvt_pk_bf16_f32 v129, v14, v15
	v_cvt_pk_bf16_f32 v130, v8, v9
	v_cvt_pk_bf16_f32 v131, v10, v11
	global_store_dwordx4 v174, v[128:131], s[60:61]
	global_store_dwordx4 v175, v[4:7], s[100:101] offset:512
	global_store_dwordx4 v175, v[0:3], s[100:101] offset:528
	v_cvt_pk_bf16_f32 v132, v4, v5
	v_cvt_pk_bf16_f32 v133, v6, v7
	v_cvt_pk_bf16_f32 v134, v0, v1
	v_cvt_pk_bf16_f32 v135, v2, v3
	global_store_dwordx4 v174, v[132:135], s[60:61] offset:256
	s_branch .Lwin_done
